# B operand (FFN-up weights) stored k-block-major so each LDS-DMA instruction reads 1 KiB contiguous; 4 B loads share one address via offset
# speedup vs baseline: 1.0233x; 1.0233x over previous
; DI unsigned xb_add(unsigned* p, unsigned v) { return __hip_atomic_fetch_add(p, v, __ATOMIC_RELAXED, __HIP_MEMORY_SCOPE_AGENT); }
; DI unsigned xb_xcc_id() { return (unsigned)__builtin_amdgcn_s_getreg((3 << 11) | 20) & 0xFu; }
; __global__ void __launch_bounds__(256, 2) fwd_kernel(Params p) {
;   extern __shared__ __attribute__((aligned(16))) char smem[];
;   cg::grid_group grid = cg::this_grid();
;   const int G = gridDim.x, bid = blockIdx.x, NW = G * 4;
;   __shared__ uint4 xb_words;
;   if (threadIdx.x == 0) xb_words = make_uint4(0u, 0u, 0u, 0u);
;   __syncthreads();
;   unsigned* const xbar = (unsigned*)(p.ws + OFF_BAR);
;   const unsigned xb_x = xb_xcc_id();
;   if (threadIdx.x == 0) (void)xb_add(&xbar[XB_XCNT(xb_x)], 1u);
_Z10fwd_kernel6Params:
	s_load_dwordx4 s[4:7], s[0:1], 0x100
	v_and_b32_e32 v187, 0x3ff, v0
	v_writelane_b32 v252, s2, 0
	s_mov_b32 s101, 0
	s_add_u32 s2, s0, 0x110
	s_waitcnt lgkmcnt(0)
	v_writelane_b32 v252, s4, 1
	s_nop 1
	v_writelane_b32 v252, s5, 2
	v_writelane_b32 v252, s6, 3
	v_writelane_b32 v252, s7, 4
	v_writelane_b32 v252, s0, 5
	s_addc_u32 s3, s1, 0
	s_nop 0
	v_writelane_b32 v252, s1, 6
	v_writelane_b32 v252, s2, 7
	s_nop 1
	v_writelane_b32 v252, s3, 8
	v_cmp_eq_u32_e64 s[2:3], 0, v187
	s_mov_b64 s[0:1], exec
	s_nop 0
	v_writelane_b32 v252, s2, 9
	s_nop 1
	v_writelane_b32 v252, s3, 10
	s_and_b64 s[2:3], s[0:1], s[2:3]
	s_mov_b64 exec, s[2:3]
	v_mov_b32_e32 v2, 0
	v_mov_b32_e32 v3, v2
	v_mov_b32_e32 v4, v2
	v_mov_b32_e32 v5, v2
	ds_write_b128 v2, v[2:5]
	s_or_b64 exec, exec, s[0:1]
	v_readlane_b32 s0, v252, 5
	v_readlane_b32 s1, v252, 6
	s_load_dword s44, s[0:1], 0x110
	v_readlane_b32 s0, v252, 1
	v_readlane_b32 s2, v252, 3
	s_waitcnt lgkmcnt(0)
	s_barrier
	v_readlane_b32 s1, v252, 2
	s_add_u32 s0, s0, 0x309c000
	s_getreg_b32 s2, hwreg(HW_REG_XCC_ID, 0, 4)
	v_readlane_b32 s3, v252, 4
	s_addc_u32 s1, s1, 0
	s_and_b32 s6, s2, 15
	s_mov_b64 s[2:3], exec
	v_readlane_b32 s4, v252, 9
	v_readlane_b32 s5, v252, 10
	s_and_b64 s[4:5], s[2:3], s[4:5]
	s_mov_b64 exec, s[4:5]
	s_cbranch_execz .LBB0_5
	s_mov_b64 s[4:5], exec
	v_mbcnt_lo_u32_b32 v1, s4, 0
	v_mbcnt_hi_u32_b32 v1, s5, v1
	v_cmp_eq_u32_e32 vcc, 0, v1
	s_and_b64 s[8:9], exec, vcc
	s_mov_b64 exec, s[8:9]
	s_cbranch_execz .LBB0_5
	s_lshl_b32 s7, s6, 8
	s_bcnt1_i32_b64 s4, s[4:5]
	v_mov_b32_e32 v1, s7
	v_mov_b32_e32 v2, s4
	global_atomic_add v1, v2, s[0:1] offset:1024

; #define LAS __attribute__((address_space(3)))
;     ...
;   const int lane = tid & 63, wid = __builtin_amdgcn_readfirstlane(tid >> 6), wr = wid >> 1, wc = wid & 1;
;   const int m0 = mt * 128, n0 = nt * 256;
;   const int r = lane & 31, h = lane >> 5, key = (r >> 2) & 3;
;   constexpr int STG = 24576;
;   const int rowl = lane >> 2, cch = (lane & 3) ^ ((lane >> 4) & 3);
;   const unsigned voffA = (unsigned)(rowl * lda * 2 + cch * 16), voffB = (unsigned)(rowl * K * 2 + cch * 16);
;   const char* Abase = (const char*)(A + (size_t)m0 * lda) + (size_t)(wid * 2) * 32 * lda;
;   const char* Bbase = (const char*)(Bt + (size_t)n0 * K) + (size_t)(wid * 4) * 32 * K;
;   const size_t ablk = (size_t)32 * lda, bblk = (size_t)32 * K;
;   LAS char* lds = (LAS char*)smem;
;   LAS char* ldsA = lds + (wid * 2) * 1024;
;   LAS char* ldsB = lds + 8192 + (wid * 4) * 1024;
;     ...
;   const int x0 = ((0 + h) ^ key) * 16, x1 = ((2 + h) ^ key) * 16;
;   const int a_rd = (wr * 64 + r) * 64, b_rd = 8192 + (wc * 128 + r) * 64;
;   f32x16 acc[2][4];
; #pragma unroll
;   for (int i = 0; i < 2; ++i)
; #pragma unroll
;     for (int j = 0; j < 4; ++j)
; #pragma unroll
;       for (int e = 0; e < 16; ++e) acc[i][j][e] = 0.f;
;   const int nk = K >> 5;
;   DMA_STEP_(0, 0);
;   DMA_STEP_(1, STG);
;   asm volatile("s_waitcnt vmcnt(6)" ::: "memory");
;   __builtin_amdgcn_s_barrier();
;   asm volatile("" ::: "memory");
.LBB0_271:
	s_mul_hi_i32 s10, s14, 0x2e8ba2e9
	s_lshr_b32 s11, s10, 31
	s_ashr_i32 s10, s10, 4
	s_add_i32 s10, s10, s11
	v_readlane_b32 s15, v252, 18
	s_mul_i32 s11, s10, 0xffffffa8
	s_lshl_b32 s10, s10, s15
	v_readlane_b32 s15, v252, 41
	s_add_i32 s10, s10, s15
	s_lshr_b32 s15, s10, 31
	s_add_i32 s15, s10, s15
	s_and_b32 s18, s15, -2
	s_add_i32 s11, s11, s14
	s_sub_i32 s10, s10, s18
	s_mul_i32 s22, s10, 11
	s_ashr_i32 s10, s11, 3
	v_mov_b32_e32 v189, v188
	s_lshl_b32 s15, s15, 2
	s_add_i32 s22, s22, s10
	s_and_b32 s15, s15, -8
	v_readfirstlane_b32 s10, v189
	s_and_b32 s18, s14, 7
	s_ashr_i32 s11, s10, 6
	s_or_b32 s15, s15, s18
	s_lshl_b32 s18, s11, 1
	s_ashr_i32 s19, s18, 31
	s_lshl_b64 s[28:29], s[18:19], 15
	s_lshl_b32 s18, s11, 2
	s_ashr_i32 s19, s18, 31
	s_ashr_i32 s10, s10, 1
	s_lshl_b32 s46, s15, 7
	s_lshl_b32 s66, s22, 8
	v_and_b32_e32 v0, 31, v189
	s_lshl_b64 s[74:75], s[18:19], 10
	s_lshl_b32 s18, s11, 12
	s_andn2_b32 s10, s10, 63
	v_lshlrev_b32_e32 v3, 4, v189
	s_ashr_i32 s47, s46, 31
	s_ashr_i32 s67, s66, 31
	s_add_i32 s19, s18, 16
	v_or_b32_e32 v197, s10, v0
	s_lshl_b32 s10, s11, 7
	v_lshlrev_b32_e32 v2, 9, v189
	v_bitop3_b32 v3, v3, 48, v189 bitop3:0x48
	s_lshl_b64 s[20:21], s[46:47], 11
	s_lshl_b64 s[40:41], s[66:67], 6
	s_add_i32 s23, s19, 0x2000
	s_and_b32 s18, s10, 0x80
	s_movk_i32 s10, 0x7800
	v_or_b32_e32 v4, s18, v0
	v_and_or_b32 v0, v2, s10, v3
	v_lshlrev_b32_e32 v10, 4, v189
	v_and_b32_e32 v10, 0x3c0, v10
	v_or_b32_e32 v10, v10, v3
	v_mov_b32_e32 v11, 0
	s_add_u32 s10, s42, s20
	s_addc_u32 s20, s43, s21
	s_add_u32 s28, s10, s28
	s_addc_u32 s29, s20, s29
	s_add_u32 s10, s87, s40
	s_addc_u32 s21, s76, s41
	s_lshl_b32 s11, s11, 11
	s_sub_i32 s20, s19, s11
	s_mov_b32 m0, s20
	v_lshl_add_u64 v[192:193], s[28:29], 0, v[0:1]
	global_load_lds_dwordx4 v0, s[28:29]
	s_add_i32 m0, s20, 0x400
	s_add_u32 s28, s10, s74
	v_lshl_add_u64 v[2:3], v[192:193], 0, s[72:73]
	s_addc_u32 s29, s21, s75
	global_load_lds_dwordx4 v[2:3], off
	v_lshl_add_u64 v[194:195], s[28:29], 0, v[10:11]
	s_mov_b32 m0, s23
	s_mov_b64 s[10:11], 0x8040
	global_load_lds_dwordx4 v[194:195], off
	global_load_lds_dwordx4 v[194:195], off offset:1024
	global_load_lds_dwordx4 v[194:195], off offset:2048
	global_load_lds_dwordx4 v[194:195], off offset:3072
	s_add_i32 m0, s20, 0x6000
	v_lshl_add_u64 v[2:3], v[192:193], 0, 64
	global_load_lds_dwordx4 v[2:3], off
	v_lshl_add_u64 v[2:3], v[192:193], 0, s[10:11]
	s_add_i32 m0, s20, 0x6400
	v_lshrrev_b32_e32 v5, 5, v189
	global_load_lds_dwordx4 v[2:3], off
	s_mov_b32 s100, 0x58000
	s_add_i32 m0, s19, 0x8000
	v_lshl_add_u64 v[2:3], v[194:195], 0, s[100:101]
	global_load_lds_dwordx4 v[2:3], off
	global_load_lds_dwordx4 v[2:3], off offset:1024
	global_load_lds_dwordx4 v[2:3], off offset:2048
	global_load_lds_dwordx4 v[2:3], off offset:3072
	v_bfe_u32 v6, v189, 2, 2
	v_lshl_add_u64 v[194:195], v[2:3], 0, s[100:101]
	v_bfe_u32 v196, v189, 5, 1
	s_waitcnt vmcnt(6)
	s_barrier
	v_bitop3_b32 v2, v5, v6, 1 bitop3:0x6c
	v_lshlrev_b32_e32 v219, 4, v2
	v_bitop3_b32 v2, v196, v6, 2 bitop3:0x36
	v_mov_b32_e32 v66, 0
	v_lshlrev_b32_e32 v218, 6, v197
	v_lshlrev_b32_e32 v0, 6, v4
	v_lshlrev_b32_e32 v220, 4, v2
	s_mov_b32 s23, 0xc000
	s_mov_b32 s28, 0
	s_mov_b32 s21, 0
	v_mov_b32_e32 v67, v66
	v_mov_b32_e32 v68, v66
	v_mov_b32_e32 v69, v66
	v_mov_b32_e32 v70, v66
	v_mov_b32_e32 v71, v66
	v_mov_b32_e32 v72, v66
	v_mov_b32_e32 v73, v66
	v_mov_b32_e32 v74, v66
	v_mov_b32_e32 v75, v66
	v_mov_b32_e32 v76, v66
	v_mov_b32_e32 v77, v66
	v_mov_b32_e32 v78, v66
	v_mov_b32_e32 v79, v66
	v_mov_b32_e32 v80, v66
	v_mov_b32_e32 v81, v66
	v_mov_b32_e32 v82, v66
	v_mov_b32_e32 v83, v66
	v_mov_b32_e32 v84, v66
	v_mov_b32_e32 v85, v66
	v_mov_b32_e32 v86, v66
	v_mov_b32_e32 v87, v66
	v_mov_b32_e32 v88, v66
	v_mov_b32_e32 v89, v66
	s_waitcnt vmcnt(0)
	v_mov_b32_e32 v90, v66
	v_mov_b32_e32 v91, v66
	v_mov_b32_e32 v92, v66
	v_mov_b32_e32 v93, v66
	v_mov_b32_e32 v94, v66
	v_mov_b32_e32 v95, v66
	v_mov_b32_e32 v96, v66
	v_mov_b32_e32 v97, v66
	v_mov_b32_e32 v18, v66
	v_mov_b32_e32 v19, v66
	v_mov_b32_e32 v20, v66
	v_mov_b32_e32 v21, v66
	v_mov_b32_e32 v22, v66
	v_mov_b32_e32 v23, v66
	v_mov_b32_e32 v24, v66
	v_mov_b32_e32 v25, v66
	v_mov_b32_e32 v26, v66
	v_mov_b32_e32 v27, v66
	v_mov_b32_e32 v28, v66
	v_mov_b32_e32 v29, v66
	v_mov_b32_e32 v30, v66
	v_mov_b32_e32 v31, v66
	v_mov_b32_e32 v32, v66
	v_mov_b32_e32 v33, v66
	v_mov_b32_e32 v2, v66
	v_mov_b32_e32 v3, v66
	v_mov_b32_e32 v4, v66
	v_mov_b32_e32 v5, v66
	v_mov_b32_e32 v6, v66
	v_mov_b32_e32 v7, v66
	v_mov_b32_e32 v8, v66
	v_mov_b32_e32 v9, v66
	v_mov_b32_e32 v10, v66
	v_mov_b32_e32 v11, v66
	v_mov_b32_e32 v12, v66
	v_mov_b32_e32 v13, v66
	v_mov_b32_e32 v14, v66
	v_mov_b32_e32 v15, v66
	v_mov_b32_e32 v16, v66
	v_mov_b32_e32 v17, v66
	v_mov_b32_e32 v114, v66
	v_mov_b32_e32 v115, v66
	v_mov_b32_e32 v116, v66
	v_mov_b32_e32 v117, v66
	v_mov_b32_e32 v118, v66
	v_mov_b32_e32 v119, v66
	v_mov_b32_e32 v120, v66
	v_mov_b32_e32 v121, v66
	v_mov_b32_e32 v122, v66
	v_mov_b32_e32 v123, v66
	v_mov_b32_e32 v124, v66
	v_mov_b32_e32 v125, v66
	v_mov_b32_e32 v126, v66
	v_mov_b32_e32 v127, v66
	v_mov_b32_e32 v128, v66
	v_mov_b32_e32 v129, v66
	v_mov_b32_e32 v98, v66
	v_mov_b32_e32 v99, v66
	v_mov_b32_e32 v100, v66
	v_mov_b32_e32 v101, v66
	v_mov_b32_e32 v102, v66
	v_mov_b32_e32 v103, v66
	v_mov_b32_e32 v104, v66
	v_mov_b32_e32 v105, v66
	v_mov_b32_e32 v106, v66
	v_mov_b32_e32 v107, v66
	v_mov_b32_e32 v108, v66
	v_mov_b32_e32 v109, v66
	v_mov_b32_e32 v110, v66
	v_mov_b32_e32 v111, v66
	v_mov_b32_e32 v112, v66
	v_mov_b32_e32 v113, v66
	v_mov_b32_e32 v50, v66
	v_mov_b32_e32 v51, v66
	v_mov_b32_e32 v52, v66
	v_mov_b32_e32 v53, v66
	v_mov_b32_e32 v54, v66
	v_mov_b32_e32 v55, v66
	v_mov_b32_e32 v56, v66
	v_mov_b32_e32 v57, v66
	v_mov_b32_e32 v58, v66
	v_mov_b32_e32 v59, v66
	v_mov_b32_e32 v60, v66
	v_mov_b32_e32 v61, v66
	v_mov_b32_e32 v62, v66
	v_mov_b32_e32 v63, v66
	v_mov_b32_e32 v64, v66
	v_mov_b32_e32 v65, v66
	v_mov_b32_e32 v34, v66
	v_mov_b32_e32 v35, v66
	v_mov_b32_e32 v36, v66
	v_mov_b32_e32 v37, v66
	v_mov_b32_e32 v38, v66
	v_mov_b32_e32 v39, v66
	v_mov_b32_e32 v40, v66
	v_mov_b32_e32 v41, v66
	v_mov_b32_e32 v42, v66
	v_mov_b32_e32 v43, v66
	v_mov_b32_e32 v44, v66
	v_mov_b32_e32 v45, v66
	v_mov_b32_e32 v46, v66
	v_mov_b32_e32 v47, v66
	v_mov_b32_e32 v48, v66
	v_mov_b32_e32 v49, v66
; #define LAS __attribute__((address_space(3)))
; DI f32x16 mfma32(bf16x8 a, bf16x8 b, f32x16 c) { return __builtin_amdgcn_mfma_f32_32x32x16_bf16(a, b, c, 0, 0, 0); }
;     ...
;   for (int kt = 0; kt < nk; ++kt) {
;     const int kn = (kt + 2 < nk) ? (kt + 2) : (nk - 1);
;     const LAS char* cur = lds + s0;
;     bf16x8 af[2][2], bfr[2][4];
; #pragma unroll
;     for (int kk = 0; kk < 2; ++kk) {
;       const int xo = kk ? x1 : x0;
;       af[kk][0] = *(const LAS bf16x8*)(cur + a_rd + xo);
;       bfr[kk][0] = *(const LAS bf16x8*)(cur + b_rd + xo);
;       bfr[kk][1] = *(const LAS bf16x8*)(cur + b_rd + 2048 + xo);
;       af[kk][1] = *(const LAS bf16x8*)(cur + a_rd + 2048 + xo);
;       bfr[kk][2] = *(const LAS bf16x8*)(cur + b_rd + 4096 + xo);
;       bfr[kk][3] = *(const LAS bf16x8*)(cur + b_rd + 6144 + xo);
;     }
;     DMA_STEP_(kn, s2);
; #pragma unroll
;     for (int kk = 0; kk < 2; ++kk) {
;       acc[0][0] = mfma32(bfr[kk][0], af[kk][0], acc[0][0]); acc[0][1] = mfma32(bfr[kk][1], af[kk][0], acc[0][1]);
;       acc[1][0] = mfma32(bfr[kk][0], af[kk][1], acc[1][0]); acc[1][1] = mfma32(bfr[kk][1], af[kk][1], acc[1][1]);
;       acc[0][2] = mfma32(bfr[kk][2], af[kk][0], acc[0][2]); acc[0][3] = mfma32(bfr[kk][3], af[kk][0], acc[0][3]);
;       acc[1][2] = mfma32(bfr[kk][2], af[kk][1], acc[1][2]); acc[1][3] = mfma32(bfr[kk][3], af[kk][1], acc[1][3]);
;     }
;     __builtin_amdgcn_sched_group_barrier(0x100, 12, 0);
;     __builtin_amdgcn_sched_group_barrier(0x010, 6, 0);
;     __builtin_amdgcn_sched_group_barrier(0x008, 16, 0);
;     asm volatile("s_waitcnt vmcnt(6) lgkmcnt(0)" ::: "memory");
;     __builtin_amdgcn_s_barrier();
;     asm volatile("" ::: "memory");
;     s0 = (s0 == 2 * STG) ? 0 : s0 + STG;
;     s2 = (s2 == 2 * STG) ? 0 : s2 + STG;
.LBB0_272:
	s_add_i32 s11, s28, 16
	v_add_u32_e32 v142, s11, v0
	s_min_u32 s10, s21, 29
	v_add_u32_e32 v140, v142, v219
	ds_read_b128 v[182:185], v140 offset:8192
	ds_read_b128 v[178:181], v140 offset:10240
	ds_read_b128 v[174:177], v140 offset:12288
	ds_read_b128 v[170:173], v140 offset:14336
	s_lshl_b32 s70, s10, 6
	v_add_u32_e32 v138, s11, v218
	v_lshl_add_u64 v[222:223], v[192:193], 0, s[70:71]
	s_add_i32 s10, s20, s23
	v_add_u32_e32 v139, v138, v219
	v_add_u32_e32 v143, v138, v220
	v_add_u32_e32 v150, v142, v220
	v_lshl_add_u64 v[224:225], v[222:223], 0, s[24:25]
	s_mov_b32 m0, s10
	ds_read_b128 v[154:157], v139
	ds_read_b128 v[158:161], v139 offset:2048
	ds_read_b128 v[138:141], v143
	ds_read_b128 v[162:165], v150 offset:8192
	ds_read_b128 v[166:169], v150 offset:10240
	ds_read_b128 v[142:145], v143 offset:2048
	ds_read_b128 v[146:149], v150 offset:12288
	ds_read_b128 v[150:153], v150 offset:14336
	global_load_lds_dwordx4 v[224:225], off
	v_lshl_add_u64 v[222:223], v[222:223], 0, s[38:39]
	s_add_i32 m0, s10, 0x400
	s_add_i32 s10, s19, s23
	global_load_lds_dwordx4 v[222:223], off
	s_mul_i32 s100, s70, 0x1600
	v_lshl_add_u64 v[224:225], v[194:195], 0, s[100:101]
	s_add_i32 m0, s10, 0x2000
	s_nop 0
	global_load_lds_dwordx4 v[224:225], off
	global_load_lds_dwordx4 v[224:225], off offset:1024
	global_load_lds_dwordx4 v[224:225], off offset:2048
	global_load_lds_dwordx4 v[224:225], off offset:3072
	s_add_i32 s10, s28, 0x6000
	s_waitcnt lgkmcnt(0)
	v_mfma_f32_32x32x16_bf16 v[66:81], v[182:185], v[154:157], v[66:81]
	s_cmpk_lg_u32 s28, 0xc000
	s_cselect_b32 s28, s10, 0
	s_add_i32 s10, s23, 0x6000
	s_cmpk_lg_u32 s23, 0xc000
	s_cselect_b32 s23, s10, 0
	s_add_i32 s10, s21, 1
	s_min_u32 s10, s10, 29
	v_mfma_f32_32x32x16_bf16 v[82:97], v[178:181], v[154:157], v[82:97]
	s_add_i32 s11, s28, 16
	s_lshl_b32 s70, s10, 6
	v_lshl_add_u64 v[222:223], v[192:193], 0, s[70:71]
	s_add_i32 s10, s20, s23
	s_waitcnt vmcnt(6) lgkmcnt(0)
	s_barrier
	v_mfma_f32_32x32x16_bf16 v[18:33], v[182:185], v[158:161], v[18:33]
	v_lshl_add_u64 v[224:225], v[222:223], 0, s[24:25]
	s_mov_b32 m0, s10
	v_lshl_add_u64 v[222:223], v[222:223], 0, s[38:39]
	v_mfma_f32_32x32x16_bf16 v[2:17], v[178:181], v[158:161], v[2:17]
	v_mfma_f32_32x32x16_bf16 v[114:129], v[174:177], v[154:157], v[114:129]
	v_mfma_f32_32x32x16_bf16 v[98:113], v[170:173], v[154:157], v[98:113]
	v_mfma_f32_32x32x16_bf16 v[50:65], v[174:177], v[158:161], v[50:65]
	v_mfma_f32_32x32x16_bf16 v[34:49], v[170:173], v[158:161], v[34:49]
	v_mfma_f32_32x32x16_bf16 v[66:81], v[162:165], v[138:141], v[66:81]
	v_mfma_f32_32x32x16_bf16 v[82:97], v[166:169], v[138:141], v[82:97]
	v_mfma_f32_32x32x16_bf16 v[18:33], v[162:165], v[142:145], v[18:33]
	v_mfma_f32_32x32x16_bf16 v[2:17], v[166:169], v[142:145], v[2:17]
	v_mfma_f32_32x32x16_bf16 v[114:129], v[146:149], v[138:141], v[114:129]
	v_mfma_f32_32x32x16_bf16 v[98:113], v[150:153], v[138:141], v[98:113]
	v_add_u32_e32 v138, s11, v218
	v_add_u32_e32 v139, v138, v219
	v_mfma_f32_32x32x16_bf16 v[50:65], v[146:149], v[142:145], v[50:65]
	v_mfma_f32_32x32x16_bf16 v[34:49], v[150:153], v[142:145], v[34:49]
	v_add_u32_e32 v142, s11, v0
	v_add_u32_e32 v140, v142, v219
	v_add_u32_e32 v143, v138, v220
	v_add_u32_e32 v150, v142, v220
	ds_read_b128 v[158:161], v139
	ds_read_b128 v[182:185], v140 offset:8192
	ds_read_b128 v[178:181], v140 offset:10240
	ds_read_b128 v[162:165], v139 offset:2048
	ds_read_b128 v[174:177], v140 offset:12288
	ds_read_b128 v[170:173], v140 offset:14336
	ds_read_b128 v[138:141], v143
	ds_read_b128 v[166:169], v150 offset:8192
	ds_read_b128 v[154:157], v150 offset:10240
	ds_read_b128 v[142:145], v143 offset:2048
	ds_read_b128 v[146:149], v150 offset:12288
	ds_read_b128 v[150:153], v150 offset:14336
	global_load_lds_dwordx4 v[224:225], off
	s_add_i32 m0, s10, 0x400
	s_add_i32 s10, s19, s23
	global_load_lds_dwordx4 v[222:223], off
	s_mul_i32 s100, s70, 0x1600
	v_lshl_add_u64 v[224:225], v[194:195], 0, s[100:101]
	s_add_i32 m0, s10, 0x2000
	s_nop 0
	global_load_lds_dwordx4 v[224:225], off
	global_load_lds_dwordx4 v[224:225], off offset:1024
	global_load_lds_dwordx4 v[224:225], off offset:2048
	global_load_lds_dwordx4 v[224:225], off offset:3072
	s_add_i32 s10, s28, 0x6000
	s_waitcnt lgkmcnt(0)
	v_mfma_f32_32x32x16_bf16 v[66:81], v[182:185], v[158:161], v[66:81]
	s_cmpk_lg_u32 s28, 0xc000
	s_cselect_b32 s28, s10, 0
	s_add_i32 s10, s23, 0x6000
	s_waitcnt vmcnt(6) lgkmcnt(0)
	s_barrier
; #define GAS __attribute__((address_space(1)))
; DI unsigned pk2(float a, float b) { f32x2 v = {a, b}; bf2_t r = __builtin_convertvector(v, bf2_t); return __builtin_bit_cast(unsigned, r); }
;     ...
;       acc[0][0] = mfma32(bfr[kk][0], af[kk][0], acc[0][0]); acc[0][1] = mfma32(bfr[kk][1], af[kk][0], acc[0][1]);
;       acc[1][0] = mfma32(bfr[kk][0], af[kk][1], acc[1][0]); acc[1][1] = mfma32(bfr[kk][1], af[kk][1], acc[1][1]);
;       acc[0][2] = mfma32(bfr[kk][2], af[kk][0], acc[0][2]); acc[0][3] = mfma32(bfr[kk][3], af[kk][0], acc[0][3]);
;       acc[1][2] = mfma32(bfr[kk][2], af[kk][1], acc[1][2]); acc[1][3] = mfma32(bfr[kk][3], af[kk][1], acc[1][3]);
;     }
;     __builtin_amdgcn_sched_group_barrier(0x100, 12, 0);
;     __builtin_amdgcn_sched_group_barrier(0x010, 6, 0);
;     __builtin_amdgcn_sched_group_barrier(0x008, 16, 0);
;     asm volatile("s_waitcnt vmcnt(6) lgkmcnt(0)" ::: "memory");
;     __builtin_amdgcn_s_barrier();
;     asm volatile("" ::: "memory");
;     s0 = (s0 == 2 * STG) ? 0 : s0 + STG;
;     s2 = (s2 == 2 * STG) ? 0 : s2 + STG;
;   }
;   asm volatile("s_waitcnt vmcnt(0)" ::: "memory");
;   __builtin_amdgcn_s_barrier();
;   asm volatile("" ::: "memory");
;     ...
;   {
;     const int h = lane >> 5, cl = lane & 31;
; #pragma unroll
;     for (int i = 0; i < 2; ++i)
; #pragma unroll
;       for (int j = 0; j < 4; ++j)
; #pragma unroll
;         for (int g = 0; g < 4; ++g) {
;           u32x2 w; w.x = pk2(acc[i][j][4 * g], acc[i][j][4 * g + 1]); w.y = pk2(acc[i][j][4 * g + 2], acc[i][j][4 * g + 3]);
;           *(u32x2*)(smem + (wr * 64 + i * 32 + cl) * 528 + (wc * 128 + j * 32 + 8 * g + 4 * h) * 2) = w;
;         }
;   }
;   __syncthreads();
;   int tid2 = tid; asm volatile("" : "+v"(tid2));
;   if (EPI == 0) {
; #pragma unroll
;     for (int i = 0; i < 16; ++i) {
;       const int id = tid2 + 256 * i, r = id >> 5, c8 = (id & 31) * 8;
;       const u32x4 v = *(const u32x4*)(smem + r * 528 + c8 * 2);
;       *(GAS u32x4*)(ea.out + (size_t)(m0 + r) * ea.ldo + n0 + c8) = v;
;     }
;   } else {
;     const int L = (mt < 512) ? 2048 : 256;
;     const bool first = (m0 % L) == 0, last = ((m0 + 128) % L) == 0;
;     const float* cw = ea.cw; const float* cb = ea.cb;
; #pragma unroll 1
;     for (int p = 0; p < 2; ++p) {
;       const int j8 = (tid2 & 7) * 8;
;       const int ja0 = (nt * 2 + p) * 64, ja = ja0 + j8;
	s_cmpk_lg_u32 s23, 0xc000
	v_mfma_f32_32x32x16_bf16 v[82:97], v[178:181], v[158:161], v[82:97]
	s_cselect_b32 s23, s10, 0
	s_add_i32 s21, s21, 2
	s_cmp_eq_u32 s21, 32
	v_mfma_f32_32x32x16_bf16 v[18:33], v[182:185], v[162:165], v[18:33]
	v_mfma_f32_32x32x16_bf16 v[2:17], v[178:181], v[162:165], v[2:17]
	v_mfma_f32_32x32x16_bf16 v[114:129], v[174:177], v[158:161], v[114:129]
	v_mfma_f32_32x32x16_bf16 v[98:113], v[170:173], v[158:161], v[98:113]
	v_mfma_f32_32x32x16_bf16 v[50:65], v[174:177], v[162:165], v[50:65]
	v_mfma_f32_32x32x16_bf16 v[34:49], v[170:173], v[162:165], v[34:49]
	v_mfma_f32_32x32x16_bf16 v[66:81], v[166:169], v[138:141], v[66:81]
	v_mfma_f32_32x32x16_bf16 v[82:97], v[154:157], v[138:141], v[82:97]
	v_mfma_f32_32x32x16_bf16 v[18:33], v[166:169], v[142:145], v[18:33]
	v_mfma_f32_32x32x16_bf16 v[2:17], v[154:157], v[142:145], v[2:17]
	v_mfma_f32_32x32x16_bf16 v[114:129], v[146:149], v[138:141], v[114:129]
	v_mfma_f32_32x32x16_bf16 v[98:113], v[150:153], v[138:141], v[98:113]
	v_mfma_f32_32x32x16_bf16 v[50:65], v[146:149], v[142:145], v[50:65]
	v_mfma_f32_32x32x16_bf16 v[34:49], v[150:153], v[142:145], v[34:49]
	s_cbranch_scc0 .LBB0_272
	v_mul_lo_u32 v0, v197, s55
	v_add_u32_e32 v0, 16, v0
	s_nop 1
	v_cvt_pk_bf16_f32 v66, v66, v67
	v_cvt_pk_bf16_f32 v67, v68, v69
	v_lshlrev_b32_e32 v68, 3, v196
	s_lshl_b32 s10, s18, 1
	v_add3_u32 v0, v0, v68, s10
	v_cvt_pk_bf16_f32 v68, v70, v71
	v_cvt_pk_bf16_f32 v69, v72, v73
	s_waitcnt vmcnt(0)
	s_barrier
	ds_write2_b64 v0, v[66:67], v[68:69] offset1:2
	v_cvt_pk_bf16_f32 v66, v74, v75
	v_cvt_pk_bf16_f32 v67, v76, v77
	v_cvt_pk_bf16_f32 v68, v78, v79
	v_cvt_pk_bf16_f32 v69, v80, v81
	ds_write2_b64 v0, v[66:67], v[68:69] offset0:4 offset1:6
	v_cvt_pk_bf16_f32 v66, v82, v83
	v_cvt_pk_bf16_f32 v67, v84, v85
	v_cvt_pk_bf16_f32 v68, v86, v87
	v_cvt_pk_bf16_f32 v69, v88, v89
	ds_write2_b64 v0, v[66:67], v[68:69] offset0:8 offset1:10
	v_cvt_pk_bf16_f32 v66, v90, v91
	v_cvt_pk_bf16_f32 v67, v92, v93
	v_cvt_pk_bf16_f32 v68, v94, v95
	v_cvt_pk_bf16_f32 v69, v96, v97
	ds_write2_b64 v0, v[66:67], v[68:69] offset0:12 offset1:14
	v_cvt_pk_bf16_f32 v66, v114, v115
	v_cvt_pk_bf16_f32 v67, v116, v117
	v_cvt_pk_bf16_f32 v68, v118, v119
	v_cvt_pk_bf16_f32 v69, v120, v121
	ds_write2_b64 v0, v[66:67], v[68:69] offset0:16 offset1:18
	v_cvt_pk_bf16_f32 v66, v122, v123
	v_cvt_pk_bf16_f32 v67, v124, v125
	v_cvt_pk_bf16_f32 v68, v126, v127
	v_cvt_pk_bf16_f32 v69, v128, v129
	ds_write2_b64 v0, v[66:67], v[68:69] offset0:20 offset1:22
	v_cvt_pk_bf16_f32 v66, v98, v99
	v_cvt_pk_bf16_f32 v67, v100, v101
	v_cvt_pk_bf16_f32 v68, v102, v103
	v_cvt_pk_bf16_f32 v69, v104, v105
	ds_write2_b64 v0, v[66:67], v[68:69] offset0:24 offset1:26
	v_cvt_pk_bf16_f32 v66, v106, v107
	v_cvt_pk_bf16_f32 v67, v108, v109
	v_cvt_pk_bf16_f32 v68, v110, v111
	v_cvt_pk_bf16_f32 v69, v112, v113
	ds_write2_b64 v0, v[66:67], v[68:69] offset0:28 offset1:30
	v_add_u32_e32 v0, 0x4000, v0
	v_cvt_pk_bf16_f32 v2, v2, v3
	v_cvt_pk_bf16_f32 v3, v4, v5
	v_cvt_pk_bf16_f32 v4, v6, v7
	v_cvt_pk_bf16_f32 v5, v8, v9
	ds_write2_b64 v0, v[2:3], v[4:5] offset0:72 offset1:74
	v_cvt_pk_bf16_f32 v2, v10, v11
	v_cvt_pk_bf16_f32 v3, v12, v13
	v_cvt_pk_bf16_f32 v4, v14, v15
	v_cvt_pk_bf16_f32 v5, v16, v17
	ds_write2_b64 v0, v[2:3], v[4:5] offset0:76 offset1:78
	v_cvt_pk_bf16_f32 v2, v50, v51
	v_cvt_pk_bf16_f32 v3, v52, v53
	v_cvt_pk_bf16_f32 v4, v54, v55
	v_cvt_pk_bf16_f32 v5, v56, v57
	s_cmpk_lt_i32 s15, 0x200
	ds_write2_b64 v0, v[2:3], v[4:5] offset0:80 offset1:82
	v_cvt_pk_bf16_f32 v2, v58, v59
	v_cvt_pk_bf16_f32 v3, v60, v61
	v_cvt_pk_bf16_f32 v4, v62, v63
	v_cvt_pk_bf16_f32 v5, v64, v65
	s_cselect_b32 s10, 0x7ff, s78
	v_cvt_pk_bf16_f32 v18, v18, v19
	v_cvt_pk_bf16_f32 v19, v20, v21
	v_cvt_pk_bf16_f32 v20, v22, v23
	v_cvt_pk_bf16_f32 v21, v24, v25
	ds_write2_b64 v0, v[2:3], v[4:5] offset0:84 offset1:86
	v_cvt_pk_bf16_f32 v2, v34, v35
	v_cvt_pk_bf16_f32 v3, v36, v37
	v_cvt_pk_bf16_f32 v4, v38, v39
	v_cvt_pk_bf16_f32 v5, v40, v41
	s_and_b32 s11, s10, s46
	ds_write2_b64 v0, v[18:19], v[20:21] offset0:64 offset1:66
	v_cvt_pk_bf16_f32 v18, v26, v27
	v_cvt_pk_bf16_f32 v19, v28, v29
	v_cvt_pk_bf16_f32 v20, v30, v31
	v_cvt_pk_bf16_f32 v21, v32, v33
	ds_write2_b64 v0, v[2:3], v[4:5] offset0:88 offset1:90
	v_cvt_pk_bf16_f32 v2, v42, v43
	v_cvt_pk_bf16_f32 v3, v44, v45
	v_cvt_pk_bf16_f32 v4, v46, v47
	v_cvt_pk_bf16_f32 v5, v48, v49
	s_cmp_eq_u32 s11, 0
	ds_write2_b64 v0, v[18:19], v[20:21] offset0:68 offset1:70
	ds_write2_b64 v0, v[2:3], v[4:5] offset0:92 offset1:94
	s_waitcnt vmcnt(0) lgkmcnt(0)
	s_barrier
	s_cselect_b64 s[18:19], -1, 0
	s_add_i32 s11, s46, 0x80
	v_lshlrev_b32_e32 v0, 3, v189
	s_and_b32 s10, s11, s10
	v_and_b32_e32 v96, 56, v0
	s_cmp_eq_u32 s10, 0
	v_lshlrev_b32_e32 v0, 1, v96
	s_mov_b32 s40, 0
	s_cselect_b64 s[20:21], -1, 0
	s_lshl_b32 s47, s22, 7
	v_add_u32_e32 v97, 16, v0
	v_lshl_add_u64 v[90:91], s[44:45], 0, v[0:1]
	s_mov_b64 s[28:29], -1
	s_branch .LBB0_275

; DI int wt_map(int mode, int d) {
;   if (mode == 0) return d;
;   if (mode == 1) { if (d < 640) return d; if (d < 2176) return d + 32; if (d < 2208) return d - 2176 + 640; return -1; }
;   const int tile = d >> 7, w = d & 127;
;   return (w < 64) ? (tile * 64 + w) : (2816 + tile * 64 + (w - 64));
; }
; DI void wt_item(const float* __restrict__ W, int ldw, int K, bf16_t* __restrict__ Wt, int k0, int d0, int mode, char* smem, int tid) {
;   float* tile = (float*)smem;
;   __syncthreads();
;   {
;     const int j = tid & 63, kq = tid >> 6;
;     const int src = wt_map(mode, d0 + j);
; __global__ void __launch_bounds__(256, 2) fwd_kernel(Params p) {
;     ...
;           const int kt = r / nd, dt = r % nd;
;           wt_item(W, ldw, K, (bf16_t*)(ws + off), kt * 64, dt * 64, mode, smem, tid);
.LBB0_429:
	s_lshl_b32 s100, s22, 12
	s_and_b32 s10, 0xffff, s22
	v_cvt_f32_u32_e32 v0, s10
	s_and_b32 s10, s15, 0xffff
	v_cvt_f32_u32_e32 v8, s10
	s_waitcnt lgkmcnt(0)
	v_rcp_iflag_f32_e32 v7, v0
	s_barrier
	v_mul_f32_e32 v7, v8, v7
	v_trunc_f32_e32 v7, v7
	v_fma_f32 v8, -v7, v0, v8
	v_cvt_u32_f32_e32 v7, v7
	v_and_b32_e32 v8, 0x7fffffff, v8
	v_cmp_ge_f32_e32 vcc, v8, v0
	s_cmp_lg_u64 vcc, 0
	v_readfirstlane_b32 s10, v7
	s_addc_u32 s28, s10, 0
	s_mul_i32 s10, s28, s22
	s_sub_i32 s22, s15, s10
	s_lshl_b32 s10, s22, 6
	s_and_b32 s15, s10, 0xffc0
	s_cmp_lt_i32 s23, 1
	v_or_b32_e32 v0, s15, v190
	s_cbranch_scc1 .LBB0_445
	s_cmp_lg_u32 s23, 1
	s_mov_b64 s[20:21], -1
	s_cbranch_scc0 .LBB0_436
	v_and_b32_e32 v8, 0x7f, v0
	s_lshr_b32 s10, s15, 1
	v_cmp_lt_u32_e32 vcc, 63, v8
	s_and_b32 s23, s10, 0xfc0
	s_and_saveexec_b64 s[20:21], vcc
	s_xor_b64 s[20:21], exec, s[20:21]
	v_add_u32_e32 v7, s23, v8
	v_add_u32_e32 v7, 0xac0, v7
	s_andn2_saveexec_b64 s[20:21], s[20:21]
	v_or_b32_e32 v7, s23, v8
	s_or_b64 exec, exec, s[20:21]
	s_mov_b64 s[20:21], 0

; #define GAS __attribute__((address_space(1)))
; DI unsigned pk2(float a, float b) { f32x2 v = {a, b}; bf2_t r = __builtin_convertvector(v, bf2_t); return __builtin_bit_cast(unsigned, r); }
; DI void wt_item(const float* __restrict__ W, int ldw, int K, bf16_t* __restrict__ Wt, int k0, int d0, int mode, char* smem, int tid) {
;     ...
;   __syncthreads();
; #pragma unroll
;   for (int u = 0; u < 2; ++u) {
;     const int id = tid + 256 * u, j = id >> 3, k8 = (id & 7) * 8;
;     float v[8];
; #pragma unroll
;     for (int e = 0; e < 8; ++e) v[e] = tile[(k8 + e) * 65 + j];
;     u32x4 w; w.x = pk2(v[0], v[1]); w.y = pk2(v[2], v[3]); w.z = pk2(v[4], v[5]); w.w = pk2(v[6], v[7]);
;     *(GAS u32x4*)(Wt + (size_t)(d0 + j) * K + k0 + k8) = w;
;   }
; __global__ void __launch_bounds__(256, 2) fwd_kernel(Params p) {
;     ...
;         else if (item < 1024) {
;           const int idx = (item - 640) * 256 + tid;
;           const int t = idx / 48, e = idx % 48;
;           const float row = (float)(t >> 6), col = (float)(t & 63);
;           if (e < 32) { const int i = e; const float inv = exp2f(-(float)(i & 15) * (13.287712379549449f / 16.f)); const float ang = ((i < 16) ? row : col) * inv;
;             ((f32x2*)(ws + OFF_CS64))[t * 32 + i] = (f32x2){cosf(ang), sinf(ang)}; }
;           else { const int i = e - 32; const float inv = exp2f(-(float)(i & 7) * (13.287712379549449f / 8.f)); const float ang = ((i < 8) ? row : col) * inv;
;             ((f32x2*)(ws + OFF_CS32))[t * 16 + i] = (f32x2){cosf(ang), sinf(ang)}; }
.LBB0_461:
	s_or_b64 exec, exec, s[18:19]
	v_readlane_b32 s10, v250, 18
	ds_write_b32 v66, v0 offset:14560
	ds_write_b32 v66, v7 offset:15600
	v_add_u32_e32 v0, 0x400, v64
	v_readlane_b32 s11, v250, 19
	s_add_u32 s10, s10, s48
	s_waitcnt lgkmcnt(0)
	s_barrier
	ds_read2_b32 v[8:9], v64 offset1:65
	ds_read2_b32 v[10:11], v64 offset0:130 offset1:195
	ds_read2_b32 v[12:13], v0 offset0:4 offset1:69
	ds_read2_b32 v[14:15], v0 offset0:134 offset1:199
	s_addc_u32 s11, s11, s49
	s_cmp_eq_u32 s48, 0x990000
	s_cbranch_scc1 .Lmy_wt_new
	s_cmp_eq_u32 s48, 0x1490000
	s_cbranch_scc1 .Lmy_wt_new
	s_lshl_b32 s18, s22, 1
	s_add_u32 s18, s10, s18
	s_addc_u32 s19, s11, 0
	v_mov_b32_e32 v7, v1
	v_add_u32_e32 v0, s15, v61
	v_lshl_add_u64 v[16:17], s[18:19], 0, v[6:7]
	v_ashrrev_i32_e32 v7, 31, v0
	s_waitcnt lgkmcnt(0)
	v_cvt_pk_bf16_f32 v8, v8, v9
	v_cvt_pk_bf16_f32 v9, v10, v11
	v_cvt_pk_bf16_f32 v10, v12, v13
	v_cvt_pk_bf16_f32 v11, v14, v15
	v_mul_lo_u32 v7, s46, v7
	v_mul_lo_u32 v14, s47, v0
	v_mad_u64_u32 v[12:13], s[18:19], s46, v0, 0
	v_add3_u32 v13, v13, v7, v14
	ds_read2_b32 v[14:15], v65 offset1:65
	ds_read2_b32 v[18:19], v65 offset0:130 offset1:195
	v_add_u32_e32 v0, 0x400, v65
	ds_read2_b32 v[20:21], v0 offset0:4 offset1:69
	ds_read2_b32 v[22:23], v0 offset0:134 offset1:199
	v_add_u32_e32 v0, s15, v62
	v_lshl_add_u64 v[12:13], v[12:13], 1, v[16:17]
	v_ashrrev_i32_e32 v7, 31, v0
	global_store_dwordx4 v[12:13], v[8:11], off
	v_mul_lo_u32 v7, s46, v7
	v_mad_u64_u32 v[12:13], s[18:19], s46, v0, 0
	s_waitcnt lgkmcnt(0)
	v_cvt_pk_bf16_f32 v8, v14, v15
	v_mul_lo_u32 v14, s47, v0
	v_add3_u32 v13, v13, v7, v14
	v_cvt_pk_bf16_f32 v9, v18, v19
	v_cvt_pk_bf16_f32 v10, v20, v21
	v_cvt_pk_bf16_f32 v11, v22, v23
	v_lshl_add_u64 v[12:13], v[12:13], 1, v[16:17]
	global_store_dwordx4 v[12:13], v[8:11], off
	s_branch .Lmy_wt_done
.Lmy_wt_new:
	s_lshr_b32 s18, s22, 5
	s_mul_i32 s18, s18, s100
	s_add_u32 s18, s10, s18
	s_addc_u32 s19, s11, 0
	v_bfe_u32 v16, v6, 6, 1
	v_mul_lo_u32 v16, v16, s100
	v_and_b32_e32 v17, 48, v6
	v_add_u32_e32 v0, s15, v61
	v_lshl_add_u32 v0, v0, 6, v17
	v_add_u32_e32 v16, v16, v0
	s_waitcnt lgkmcnt(0)
	v_cvt_pk_bf16_f32 v8, v8, v9
	v_cvt_pk_bf16_f32 v9, v10, v11
	v_cvt_pk_bf16_f32 v10, v12, v13
	v_cvt_pk_bf16_f32 v11, v14, v15
	ds_read2_b32 v[14:15], v65 offset1:65
	ds_read2_b32 v[18:19], v65 offset0:130 offset1:195
	v_add_u32_e32 v0, 0x400, v65
	ds_read2_b32 v[20:21], v0 offset0:4 offset1:69
	ds_read2_b32 v[22:23], v0 offset0:134 offset1:199
	global_store_dwordx4 v16, v[8:11], s[18:19]
	s_waitcnt lgkmcnt(0)
	v_cvt_pk_bf16_f32 v12, v14, v15
	v_cvt_pk_bf16_f32 v13, v18, v19
	v_cvt_pk_bf16_f32 v14, v20, v21
	v_cvt_pk_bf16_f32 v15, v22, v23
	global_store_dwordx4 v16, v[12:15], s[18:19] offset:2048
.Lmy_wt_done:
	s_mov_b64 s[18:19], 0
.LBB0_462:
	s_and_b64 vcc, exec, s[18:19]
	s_cbranch_vccz .LBB0_484
	v_lshl_add_u32 v0, s14, 8, v63
	s_mov_b32 s10, 0x2aaaaaab
	v_mul_hi_i32 v7, v0, s10
	v_lshrrev_b32_e32 v8, 31, v7
	v_ashrrev_i32_e32 v7, 3, v7
	v_add_u32_e32 v7, v7, v8
	v_mul_lo_u32 v8, v7, 48
	v_sub_u32_e32 v8, v0, v8
	v_ashrrev_i32_e32 v0, 6, v7
	v_cvt_f32_i32_e32 v0, v0
	v_and_b32_e32 v9, 63, v7
	v_cvt_f32_ubyte0_e32 v9, v9
	v_cmp_lt_i32_e32 vcc, 31, v8
	s_and_saveexec_b64 s[18:19], vcc
	s_xor_b64 s[18:19], exec, s[18:19]
	s_cbranch_execz .LBB0_473
	v_and_b32_e32 v10, 7, v8
	v_cvt_f32_ubyte0_e32 v10, v10
	v_mul_f32_e32 v11, 0xbfd49a78, v10
	s_mov_b32 s10, 0xc2fc0000
	v_cmp_gt_f32_e32 vcc, s10, v11
	v_cmp_gt_u32_e64 s[46:47], 40, v8
	s_nop 0
	v_cndmask_b32_e32 v11, 0, v208, vcc
	v_fmac_f32_e32 v11, 0xbfd49a78, v10
	v_exp_f32_e32 v10, v11
	v_cndmask_b32_e64 v0, v9, v0, s[46:47]
	v_cndmask_b32_e32 v9, 0, v209, vcc
	v_ldexp_f32 v9, v10, v9
	v_mul_f32_e32 v9, v0, v9
	v_and_b32_e32 v10, 0x7fffffff, v9
	v_lshrrev_b32_e32 v0, 23, v10
	v_and_b32_e32 v11, 0x7fffff, v10
	v_cmp_nlt_f32_e64 s[20:21], |v9|, s96
	v_add_u32_e32 v14, 0xffffff88, v0
	v_or_b32_e32 v13, 0x800000, v11
	s_and_saveexec_b64 s[22:23], s[20:21]
	s_xor_b64 s[22:23], exec, s[22:23]
	s_cbranch_execz .LBB0_466
	v_cmp_lt_u32_e32 vcc, 63, v14
	v_mad_u64_u32 v[16:17], s[28:29], v13, s6, 0
	s_nop 0
	v_cndmask_b32_e32 v0, 0, v209, vcc
	v_add_u32_e32 v0, v0, v14
	v_cmp_lt_u32_e64 s[46:47], 31, v0
	s_nop 1
	v_cndmask_b32_e64 v11, 0, v210, s[46:47]
	v_add_u32_e32 v0, v11, v0
	v_cmp_lt_u32_e64 s[48:49], 31, v0
	s_nop 1
	v_cndmask_b32_e64 v11, 0, v210, s[48:49]
	v_add_u32_e32 v11, v11, v0
	v_mov_b32_e32 v0, v17
	v_mad_u64_u32 v[18:19], s[28:29], v13, s7, v[0:1]
	v_mov_b32_e32 v0, v19
	v_mad_u64_u32 v[20:21], s[28:29], v13, s31, v[0:1]
	v_mov_b32_e32 v0, v21
	v_mad_u64_u32 v[22:23], s[28:29], v13, s89, v[0:1]
	v_mov_b32_e32 v0, v23
	v_mad_u64_u32 v[24:25], s[28:29], v13, s94, v[0:1]
	v_mov_b32_e32 v0, v25
	v_mad_u64_u32 v[26:27], s[28:29], v13, s50, v[0:1]
	v_mov_b32_e32 v0, v27
	v_mad_u64_u32 v[28:29], s[28:29], v13, s51, v[0:1]
	v_cndmask_b32_e32 v12, v26, v22, vcc
	v_cndmask_b32_e32 v0, v28, v24, vcc
	v_cndmask_b32_e32 v17, v29, v26, vcc
	v_cndmask_b32_e64 v15, v0, v12, s[46:47]
	v_cndmask_b32_e64 v0, v17, v0, s[46:47]
	v_cndmask_b32_e32 v17, v24, v20, vcc
	v_cndmask_b32_e64 v12, v12, v17, s[46:47]
	v_sub_u32_e32 v19, 32, v11
	v_cmp_eq_u32_e64 s[52:53], 0, v11
	v_cndmask_b32_e32 v11, v22, v18, vcc
	v_cndmask_b32_e64 v0, v0, v15, s[48:49]
	v_cndmask_b32_e64 v15, v15, v12, s[48:49]
	v_cndmask_b32_e64 v17, v17, v11, s[46:47]
	v_alignbit_b32 v21, v0, v15, v19
	v_cndmask_b32_e64 v12, v12, v17, s[48:49]
	v_cndmask_b32_e64 v0, v21, v0, s[52:53]
	v_alignbit_b32 v18, v15, v12, v19
	v_cndmask_b32_e32 v16, v20, v16, vcc
	v_cndmask_b32_e64 v15, v18, v15, s[52:53]
	v_bfe_u32 v22, v0, 29, 1
	v_cndmask_b32_e64 v11, v11, v16, s[46:47]
	v_alignbit_b32 v18, v0, v15, 30
	v_sub_u32_e32 v23, 0, v22
	v_cndmask_b32_e64 v11, v17, v11, s[48:49]
	v_xor_b32_e32 v18, v18, v23
	v_alignbit_b32 v16, v12, v11, v19
	v_cndmask_b32_e64 v12, v16, v12, s[52:53]
	v_ffbh_u32_e32 v16, v18
	v_alignbit_b32 v15, v15, v12, 30
	v_min_u32_e32 v16, 32, v16
	v_alignbit_b32 v11, v12, v11, 30
	v_xor_b32_e32 v15, v15, v23
	v_sub_u32_e32 v17, 31, v16
	v_xor_b32_e32 v11, v11, v23
	v_alignbit_b32 v18, v18, v15, v17
	v_alignbit_b32 v11, v15, v11, v17
	v_alignbit_b32 v12, v18, v11, 9
	v_ffbh_u32_e32 v15, v12
	v_min_u32_e32 v15, 32, v15
	v_lshrrev_b32_e32 v21, 29, v0
	v_not_b32_e32 v17, v15
	v_alignbit_b32 v11, v12, v11, v17
	v_lshlrev_b32_e32 v12, 31, v21
	v_or_b32_e32 v17, 0x33000000, v12
	v_add_lshl_u32 v15, v15, v16, 23
	v_lshrrev_b32_e32 v11, 9, v11
	v_sub_u32_e32 v15, v17, v15
	v_or_b32_e32 v12, 0.5, v12
	v_lshlrev_b32_e32 v16, 23, v16
	v_or_b32_e32 v11, v15, v11
	v_lshrrev_b32_e32 v15, 9, v18
	v_sub_u32_e32 v12, v12, v16
	v_or_b32_e32 v12, v15, v12
	v_mul_f32_e32 v15, 0x3fc90fda, v12
	v_fma_f32 v16, v12, s33, -v15
	v_fmac_f32_e32 v16, 0x33a22168, v12
	v_fmac_f32_e32 v16, 0x3fc90fda, v11
	v_lshrrev_b32_e32 v0, 30, v0
	v_add_f32_e32 v12, v15, v16
	v_add_u32_e32 v11, v22, v0

; __global__ void __launch_bounds__(256, 2) fwd_kernel(Params p) {
	.amdhsa_kernel _Z10fwd_kernel6Params
		.amdhsa_group_segment_fixed_size 16
		.amdhsa_private_segment_fixed_size 0
		.amdhsa_kernarg_size 528
		.amdhsa_user_sgpr_count 2
		.amdhsa_user_sgpr_dispatch_ptr 0
		.amdhsa_user_sgpr_queue_ptr 0
		.amdhsa_user_sgpr_kernarg_segment_ptr 1
		.amdhsa_user_sgpr_dispatch_id 0
		.amdhsa_user_sgpr_kernarg_preload_length 0
		.amdhsa_user_sgpr_kernarg_preload_offset 0
		.amdhsa_user_sgpr_private_segment_size 0
		.amdhsa_uses_dynamic_stack 0
		.amdhsa_enable_private_segment 0
		.amdhsa_system_sgpr_workgroup_id_x 1
		.amdhsa_system_sgpr_workgroup_id_y 0
		.amdhsa_system_sgpr_workgroup_id_z 0
		.amdhsa_system_sgpr_workgroup_info 0
		.amdhsa_system_vgpr_workitem_id 2
		.amdhsa_next_free_vgpr 253
		.amdhsa_next_free_sgpr 102
		.amdhsa_accum_offset 256
		.amdhsa_reserve_vcc 1
		.amdhsa_float_round_mode_32 0
		.amdhsa_float_round_mode_16_64 0
		.amdhsa_float_denorm_mode_32 3
		.amdhsa_float_denorm_mode_16_64 3
		.amdhsa_dx10_clamp 1
		.amdhsa_ieee_mode 1
		.amdhsa_fp16_overflow 0
		.amdhsa_tg_split 0
		.amdhsa_exception_fp_ieee_invalid_op 0
		.amdhsa_exception_fp_denorm_src 0
		.amdhsa_exception_fp_ieee_div_zero 0
		.amdhsa_exception_fp_ieee_overflow 0
		.amdhsa_exception_fp_ieee_underflow 0
		.amdhsa_exception_fp_ieee_inexact 0
		.amdhsa_exception_int_div_zero 0
	.end_amdhsa_kernel

; __global__ void __launch_bounds__(256, 2) fwd_kernel(Params p) {
amdhsa.kernels:
  - .agpr_count:     0
    .args:
      - .offset:         0
        .size:           272
        .value_kind:     by_value
      - .offset:         272
        .size:           4
        .value_kind:     hidden_block_count_x
      - .offset:         276
        .size:           4
        .value_kind:     hidden_block_count_y
      - .offset:         280
        .size:           4
        .value_kind:     hidden_block_count_z
      - .offset:         284
        .size:           2
        .value_kind:     hidden_group_size_x
      - .offset:         286
        .size:           2
        .value_kind:     hidden_group_size_y
      - .offset:         288
        .size:           2
        .value_kind:     hidden_group_size_z
      - .offset:         290
        .size:           2
        .value_kind:     hidden_remainder_x
      - .offset:         292
        .size:           2
        .value_kind:     hidden_remainder_y
      - .offset:         294
        .size:           2
        .value_kind:     hidden_remainder_z
      - .offset:         312
        .size:           8
        .value_kind:     hidden_global_offset_x
      - .offset:         320
        .size:           8
        .value_kind:     hidden_global_offset_y
      - .offset:         328
        .size:           8
        .value_kind:     hidden_global_offset_z
      - .offset:         336
        .size:           2
        .value_kind:     hidden_grid_dims
      - .offset:         360
        .size:           8
        .value_kind:     hidden_multigrid_sync_arg
      - .offset:         392
        .size:           4
        .value_kind:     hidden_dynamic_lds_size
    .group_segment_fixed_size: 16
    .kernarg_segment_align: 8
    .kernarg_segment_size: 528
    .language:       OpenCL C
    .language_version:
      - 2
      - 0
    .max_flat_workgroup_size: 256
    .name:           _Z10fwd_kernel6Params
    .private_segment_fixed_size: 0
    .sgpr_count:     108
    .sgpr_spill_count: 162
    .symbol:         _Z10fwd_kernel6Params.kd
    .uniform_work_group_size: 1
    .uses_dynamic_stack: false
    .vgpr_count:     253
    .vgpr_spill_count: 0
    .wavefront_size: 64
